# sample attention LDS-DMA of the paged f32 cache with the default cache policy instead of nt
# speedup vs baseline: 1.0038x; 1.0038x over previous
.Lsa_stagger_done:
	v_mov_b32_e32 v250, v0
	s_barrier
	v_readlane_b32 s36, v253, 60
	v_and_b32_e32 v7, 31, v250
	v_lshl_or_b32 v2, s14, 5, v7
	v_ashrrev_i32_e32 v3, 31, v2
	v_readlane_b32 s37, v253, 61
	s_lshr_b32 s0, s14, 31
	s_add_i32 s0, s14, s0
	v_lshl_add_u64 v[2:3], v[2:3], 2, s[36:37]
	global_load_dword v252, v[2:3], off
	v_readfirstlane_b32 s18, v250
	s_ashr_i32 s16, s0, 1
	s_ashr_i32 s19, s18, 6
	s_lshl_b32 s15, s19, 3
	s_ashr_i32 s17, s15, 31
	v_bfe_u32 v9, v250, 3, 3
	v_lshlrev_b32_e32 v2, 4, v250
	v_and_b32_e32 v190, 0x70, v2
	v_and_b32_e32 v214, 63, v250
	v_lshlrev_b32_e32 v6, 4, v214
	v_readlane_b32 s38, v253, 62
	v_readlane_b32 s39, v253, 63
	v_readlane_b32 s40, v254, 0
	v_readlane_b32 s41, v254, 1
	v_readlane_b32 s42, v254, 2
	v_readlane_b32 s43, v254, 3
	v_readlane_b32 s44, v254, 4
	v_readlane_b32 s45, v254, 5
	v_readlane_b32 s46, v254, 6
	v_readlane_b32 s47, v254, 7
	v_readlane_b32 s48, v254, 8
	v_readlane_b32 s49, v254, 9
	v_readlane_b32 s50, v254, 10
	v_readlane_b32 s51, v254, 11
	s_waitcnt vmcnt(0)
	v_readlane_b32 s0, v252, 0
	s_ashr_i32 s1, s0, 31
	s_lshl_b64 s[0:1], s[0:1], 7
	s_add_u32 s4, s0, s15
	s_addc_u32 s5, s1, s17
	s_lshl_b64 s[8:9], s[4:5], 10
	v_or_b32_e32 v2, s4, v9
	s_add_u32 s4, s82, s8
	v_mov_b32_e32 v3, s5
	s_addc_u32 s5, s83, s9
	s_lshl_b32 s35, s19, 13
	s_or_b32 s8, s15, 1
	s_add_i32 s9, s35, 0
	s_ashr_i32 s10, s8, 31
	s_add_i32 m0, s9, 0xf400
	v_lshlrev_b64 v[2:3], 7, v[2:3]
	global_load_lds_dwordx4 v6, s[4:5]
	s_add_u32 s4, s0, s8
	s_addc_u32 s5, s1, s10
	s_lshl_b64 s[4:5], s[4:5], 10
	s_add_u32 s4, s82, s4
	s_addc_u32 s5, s83, s5
	s_lshl_b32 s8, s8, 10
	s_or_b32 s9, s15, 2
	s_add_i32 s8, s8, 0
	s_ashr_i32 s10, s9, 31
	s_add_i32 m0, s8, 0xf400
	v_lshl_add_u64 v[2:3], s[84:85], 0, v[2:3]
	global_load_lds_dwordx4 v6, s[4:5]
	s_add_u32 s4, s0, s9
	s_addc_u32 s5, s1, s10
	s_lshl_b64 s[4:5], s[4:5], 10
	s_add_u32 s4, s82, s4
	s_addc_u32 s5, s83, s5
	s_lshl_b32 s8, s9, 10
	s_or_b32 s9, s15, 3
	s_add_i32 s8, s8, 0
	s_ashr_i32 s10, s9, 31
	s_add_i32 m0, s8, 0xf400
	v_lshl_add_u64 v[2:3], v[2:3], 0, v[190:191]
	global_load_lds_dwordx4 v6, s[4:5]
	s_add_u32 s4, s0, s9
	s_addc_u32 s5, s1, s10
	s_lshl_b64 s[4:5], s[4:5], 10
	s_add_u32 s4, s82, s4
	s_addc_u32 s5, s83, s5
	s_lshl_b32 s8, s9, 10
	s_or_b32 s9, s15, 4
	s_add_i32 s8, s8, 0
	s_ashr_i32 s10, s9, 31
	s_add_i32 m0, s8, 0xf400
	s_nop 0
	global_load_lds_dwordx4 v6, s[4:5]
	s_add_u32 s4, s0, s9
	s_addc_u32 s5, s1, s10
	s_lshl_b64 s[4:5], s[4:5], 10
	s_add_u32 s4, s82, s4
	s_addc_u32 s5, s83, s5
	s_lshl_b32 s8, s9, 10
	s_or_b32 s9, s15, 5
	s_add_i32 s8, s8, 0
	s_ashr_i32 s10, s9, 31
	s_add_i32 m0, s8, 0xf400
	s_nop 0
	global_load_lds_dwordx4 v6, s[4:5]
	s_add_u32 s4, s0, s9
	s_addc_u32 s5, s1, s10
	s_lshl_b64 s[4:5], s[4:5], 10
	s_add_u32 s4, s82, s4
	s_addc_u32 s5, s83, s5
	s_lshl_b32 s8, s9, 10
	s_or_b32 s9, s15, 6
	s_add_i32 s8, s8, 0
	s_ashr_i32 s10, s9, 31
	s_add_i32 m0, s8, 0xf400
	s_nop 0
	global_load_lds_dwordx4 v6, s[4:5]
	s_add_u32 s4, s0, s9
	s_addc_u32 s5, s1, s10
	s_lshl_b64 s[4:5], s[4:5], 10
	s_add_u32 s4, s82, s4
	s_addc_u32 s5, s83, s5
	s_lshl_b32 s8, s9, 10
	s_or_b32 s9, s15, 7
	s_add_i32 s8, s8, 0
	s_ashr_i32 s10, s9, 31
	s_add_i32 m0, s8, 0xf400
	s_add_u32 s0, s0, s9
	s_addc_u32 s1, s1, s10
	s_lshl_b64 s[0:1], s[0:1], 10
	s_add_u32 s0, s82, s0
	global_load_lds_dwordx4 v6, s[4:5]
	s_addc_u32 s1, s83, s1
	s_lshl_b32 s4, s9, 10
	s_lshl_b32 s5, s19, 10
	s_add_i32 s4, s4, 0
	s_add_i32 s36, s5, 0
	s_add_i32 m0, s4, 0xf400
	s_add_i32 s36, s36, 0x1f400
	global_load_lds_dwordx4 v6, s[0:1]
	s_mov_b32 m0, s36
	s_movk_i32 s0, 0x30c
	global_load_lds_dwordx4 v[2:3], off
	v_cmp_gt_i32_e32 vcc, s0, v250
	s_lshl_b32 s0, s16, 3
	s_ashr_i32 s1, s0, 31
	s_add_u32 s4, s0, 0x8000
	s_addc_u32 s5, s1, 0
	s_and_saveexec_b64 s[0:1], vcc
	s_cbranch_execz .LBB0_800
	v_lshl_add_u32 v11, v250, 4, s26
	v_lshlrev_b32_e32 v8, 3, v250
	s_mov_b64 s[8:9], 0
	v_mov_b32_e32 v10, v250
	s_branch .LBB0_783

.LBB0_803:
	s_cmp_eq_u32 s10, 64
	v_lshl_add_u64 v[34:35], v[192:193], 0, s[24:25]
	s_cselect_b64 s[22:23], -1, 0
	v_lshlrev_b64 v[34:35], 7, v[34:35]
	s_add_u32 s10, s15, s24
	v_lshl_add_u64 v[38:39], v[196:197], 0, v[34:35]
	s_addc_u32 s11, s17, s25
	s_lshl_b64 s[10:11], s[10:11], 10
	v_lshl_add_u64 v[40:41], v[212:213], 0, s[10:11]
	s_and_b64 vcc, exec, s[20:21]
	s_mov_b64 s[24:25], 0x1000
	v_add_u32_e32 v207, 0xb800, v219
	v_add_u32_e32 v208, v219, v216
	ds_read_b128 v[34:37], v49
	ds_read_b128 v[182:185], v48
	ds_read_b128 v[186:189], v47
	ds_read_b128 v[202:205], v46
	s_waitcnt lgkmcnt(2)
	v_mfma_f32_16x16x32_bf16 v[226:229], v[50:53], v[34:37], 0
	v_mfma_f32_16x16x32_bf16 v[230:233], v[82:85], v[34:37], 0
	v_mfma_f32_16x16x32_bf16 v[234:237], v[114:117], v[34:37], 0
	v_mfma_f32_16x16x32_bf16 v[238:241], v[146:149], v[34:37], 0
	s_cbranch_vccz .Lsa_nd0
	s_add_i32 m0, s35, 0xf400
	s_nop 0
	global_load_lds_dwordx4 v[40:41], off
.Lsa_nd0:
	v_mfma_f32_16x16x32_bf16 v[226:229], v[54:57], v[182:185], v[226:229]
	v_mfma_f32_16x16x32_bf16 v[230:233], v[86:89], v[182:185], v[230:233]
	v_mfma_f32_16x16x32_bf16 v[234:237], v[118:121], v[182:185], v[234:237]
	v_mfma_f32_16x16x32_bf16 v[238:241], v[150:153], v[182:185], v[238:241]
	s_cbranch_vccz .Lsa_nd1
	global_load_lds_dwordx4 v[40:41], off offset:1024
.Lsa_nd1:
	ds_read_b128 v[34:37], v49 offset:16384
	ds_read_b128 v[182:185], v48 offset:16384
	s_waitcnt lgkmcnt(2)
	v_mfma_f32_16x16x32_bf16 v[226:229], v[58:61], v[186:189], v[226:229]
	v_mfma_f32_16x16x32_bf16 v[230:233], v[90:93], v[186:189], v[230:233]
	v_mfma_f32_16x16x32_bf16 v[234:237], v[122:125], v[186:189], v[234:237]
	v_mfma_f32_16x16x32_bf16 v[238:241], v[154:157], v[186:189], v[238:241]
	s_cbranch_vccz .Lsa_nd2
	global_load_lds_dwordx4 v[40:41], off offset:2048
.Lsa_nd2:
	v_mfma_f32_16x16x32_bf16 v[226:229], v[62:65], v[202:205], v[226:229]
	v_mfma_f32_16x16x32_bf16 v[230:233], v[94:97], v[202:205], v[230:233]
	v_mfma_f32_16x16x32_bf16 v[234:237], v[126:129], v[202:205], v[234:237]
	v_mfma_f32_16x16x32_bf16 v[238:241], v[158:161], v[202:205], v[238:241]
	s_cbranch_vccz .Lsa_nd3
	global_load_lds_dwordx4 v[40:41], off offset:3072
.Lsa_nd3:
	ds_read_b128 v[186:189], v47 offset:16384
	ds_read_b128 v[202:205], v46 offset:16384
	s_waitcnt lgkmcnt(2)
	v_mfma_f32_16x16x32_bf16 v[226:229], v[66:69], v[34:37], v[226:229]
	v_mfma_f32_16x16x32_bf16 v[230:233], v[98:101], v[34:37], v[230:233]
	v_mfma_f32_16x16x32_bf16 v[234:237], v[130:133], v[34:37], v[234:237]
	v_mfma_f32_16x16x32_bf16 v[238:241], v[162:165], v[34:37], v[238:241]
	s_cbranch_vccz .Lsa_nd4
	v_lshl_add_u64 v[40:41], v[40:41], 0, s[24:25]
	s_add_i32 m0, s35, 0x10400
	s_nop 0
	global_load_lds_dwordx4 v[40:41], off
.Lsa_nd4:
	v_mfma_f32_16x16x32_bf16 v[226:229], v[70:73], v[182:185], v[226:229]
	v_mfma_f32_16x16x32_bf16 v[230:233], v[102:105], v[182:185], v[230:233]
	v_mfma_f32_16x16x32_bf16 v[234:237], v[134:137], v[182:185], v[234:237]
	v_mfma_f32_16x16x32_bf16 v[238:241], v[166:169], v[182:185], v[238:241]
	s_cbranch_vccz .Lsa_nd5
	global_load_lds_dwordx4 v[40:41], off offset:1024
.Lsa_nd5:
	ds_read2_b64 v[34:37], v207 offset1:4
	ds_read2_b64 v[182:185], v207 offset0:8 offset1:12
	s_waitcnt lgkmcnt(2)
	v_mfma_f32_16x16x32_bf16 v[226:229], v[74:77], v[186:189], v[226:229]
	v_mfma_f32_16x16x32_bf16 v[230:233], v[106:109], v[186:189], v[230:233]
	v_mfma_f32_16x16x32_bf16 v[234:237], v[138:141], v[186:189], v[234:237]
	v_mfma_f32_16x16x32_bf16 v[238:241], v[170:173], v[186:189], v[238:241]
	s_cbranch_vccz .Lsa_nd6
	global_load_lds_dwordx4 v[40:41], off offset:2048
.Lsa_nd6:
	v_mfma_f32_16x16x32_bf16 v[226:229], v[78:81], v[202:205], v[226:229]
	v_mfma_f32_16x16x32_bf16 v[230:233], v[110:113], v[202:205], v[230:233]
	v_mfma_f32_16x16x32_bf16 v[234:237], v[142:145], v[202:205], v[234:237]
	v_mfma_f32_16x16x32_bf16 v[238:241], v[174:177], v[202:205], v[238:241]
	ds_read_b128 v[186:189], v225 offset:0
	ds_read_b128 v[202:205], v208 offset:47232
	s_cbranch_vccz .Lsa_nd7
	global_load_lds_dwordx4 v[40:41], off offset:3072
.Lsa_nd7:
	s_cbranch_vccz .Lsa_nd8
	s_mov_b32 m0, s36
	s_nop 0
	global_load_lds_dwordx4 v[38:39], off
